# v23 + attention accumulator init uses one v_pk_mov_b32 instead of two v_mov (1 fewer VALU per q-subtile)
# baseline (speedup 1.0000x reference)
; #define MFMA16(a, b, c) __builtin_amdgcn_mfma_f32_16x16x32_bf16((a), (b), (c), 0, 0, 0)
; DI void attn_phase(const Params& p, unsigned char* smem) {
;     ...
;                 if (2 * st_ + hf < wtiles) {
;                     const bf16_t* sK = sbuf + cur * BUF + hf * 64 * KST; const bf16_t* sV = sbuf + cur * BUF + 128 * KST + hf * 64;
;                     bf16x8 kf[4][3];
; #pragma unroll
;                     for (int kk = 0; kk < 4; ++kk)
; #pragma unroll
;                         for (int s = 0; s < 3; ++s) kf[kk][s] = *(const bf16x8*)(sK + (16 * kk + fr) * KST + 32 * s + 8 * g);
; #pragma unroll
;                     for (int qs = 0; qs < 2; ++qs) {
;                         f32x4 st[4];
;                         const float nm = -mrow[qs];
; #pragma unroll
;                         for (int kk = 0; kk < 4; ++kk) {
;                             st[kk] = (f32x4){nm, nm, nm, nm};
; #pragma unroll
;                             for (int s = 0; s < 3; ++s) st[kk] = MFMA16(kf[kk][s], qf[qs][s], st[kk]);
;                         }
;                         float mx = fmaxf(fmaxf(st[0][0], st[0][1]), fmaxf(st[0][2], st[0][3]));
; #pragma unroll
;                         for (int kk = 1; kk < 4; ++kk) mx = fmaxf(mx, fmaxf(fmaxf(st[kk][0], st[kk][1]), fmaxf(st[kk][2], st[kk][3])));
;                         const bool first = (st_ == 0 && hf == 0);
;                         if (first || __any(mx > 6.f)) {
;                             mx = fmaxf(mx, __shfl_xor(mx, 16)); mx = fmaxf(mx, __shfl_xor(mx, 32));
;                             const float shift = first ? mx : fmaxf(mx, 0.f);
;                             const float al = first ? 1.f : __builtin_amdgcn_exp2f(-shift);
;                             mrow[qs] += shift; lrow[qs] *= al;
; #pragma unroll
;                             for (int dt = 0; dt < 4; ++dt) ot[dt][qs] *= al;
; #pragma unroll
;                             for (int kk = 0; kk < 4; ++kk)
; #pragma unroll
;                                 for (int e = 0; e < 4; ++e) st[kk][e] -= shift;
.LBB0_929:
	s_or_b64 exec, exec, s[0:1]
	v_cmp_lt_i32_e32 vcc, 1, v230
	s_and_saveexec_b64 s[0:1], vcc
	s_cbranch_execz .LBB0_935
	v_xor_b32_e32 v132, 0x80000000, v203
	v_mov_b32_e32 v133, v132
	v_pk_mov_b32 v[134:135], v[132:133], v[132:133] op_sel:[0,0]
	ds_read_b128 v[112:115], v229 offset:14336
	ds_read_b128 v[116:119], v229 offset:14400
	ds_read_b128 v[120:123], v229 offset:14464
	ds_read_b128 v[100:103], v229 offset:17920
	ds_read_b128 v[104:107], v229 offset:17984
	ds_read_b128 v[108:111], v229 offset:18048
	ds_read_b128 v[96:99], v229 offset:21504
	ds_read_b128 v[92:95], v229 offset:21568
	ds_read_b128 v[88:91], v229 offset:21632
	ds_read_b128 v[84:87], v229 offset:25088
	ds_read_b128 v[80:83], v229 offset:25152
	ds_read_b128 v[76:79], v229 offset:25216
	s_waitcnt lgkmcnt(11)
	v_mfma_f32_16x16x32_bf16 v[124:127], v[112:115], v[4:7], v[132:135]
	s_waitcnt lgkmcnt(8)
	v_mfma_f32_16x16x32_bf16 v[128:131], v[100:103], v[4:7], v[132:135]
	v_mfma_f32_16x16x32_bf16 v[124:127], v[116:119], v[0:3], v[124:127]
	s_waitcnt lgkmcnt(5)
	v_mfma_f32_16x16x32_bf16 v[136:139], v[96:99], v[4:7], v[132:135]
	s_waitcnt lgkmcnt(2)
	v_mfma_f32_16x16x32_bf16 v[132:135], v[84:87], v[4:7], v[132:135]
	v_mfma_f32_16x16x32_bf16 v[128:131], v[104:107], v[0:3], v[128:131]
	v_mfma_f32_16x16x32_bf16 v[124:127], v[120:123], v[12:15], v[124:127]
	s_waitcnt lgkmcnt(1)
	v_mfma_f32_16x16x32_bf16 v[132:135], v[80:83], v[0:3], v[132:135]
	v_mfma_f32_16x16x32_bf16 v[136:139], v[92:95], v[0:3], v[136:139]
	v_mfma_f32_16x16x32_bf16 v[128:131], v[108:111], v[12:15], v[128:131]
	s_waitcnt lgkmcnt(0)
	v_mfma_f32_16x16x32_bf16 v[144:147], v[76:79], v[12:15], v[132:135]
	s_nop 3
	v_max3_f32 v132, v124, v125, v126
	v_mfma_f32_16x16x32_bf16 v[138:141], v[88:91], v[12:15], v[136:139]
	v_max3_f32 v133, v127, v128, v129
	v_max3_f32 v132, v132, v130, v131
	v_max3_f32 v134, v144, v145, v146
	v_max3_f32 v132, v132, v133, v134
	s_nop 3
	v_max3_f32 v133, v138, v139, v140
	v_max3_f32 v132, v132, v133, v141
	v_max_f32_e32 v132, v132, v147
	v_cmp_lt_f32_e32 vcc, s34, v132
	s_cbranch_vccz .LBB0_932
	v_and_b32_e32 v134, 64, v251
	v_xor_b32_e32 v133, 16, v251
	v_add_u32_e32 v134, 64, v134
	v_cmp_lt_i32_e32 vcc, v133, v134
	s_nop 1
	v_cndmask_b32_e32 v133, v251, v133, vcc
	v_lshlrev_b32_e32 v133, 2, v133
	ds_bpermute_b32 v133, v133, v132
	v_max_f32_e32 v132, v132, v132
	s_waitcnt lgkmcnt(0)
	v_max_f32_e32 v133, v133, v133
	v_max_f32_e32 v132, v132, v133
	v_xor_b32_e32 v133, 32, v251
	v_cmp_lt_i32_e32 vcc, v133, v134
	s_nop 1
	v_cndmask_b32_e32 v133, v251, v133, vcc
	v_lshlrev_b32_e32 v133, 2, v133
	ds_bpermute_b32 v133, v133, v132
	s_waitcnt lgkmcnt(0)
	v_max3_f32 v133, v132, v133, 0
	v_exp_f32_e64 v132, -v133
	v_add_f32_e32 v203, v203, v133
	v_sub_f32_e32 v124, v124, v133
	v_sub_f32_e32 v125, v125, v133
	v_mul_f32_e32 v200, v200, v132
	v_pk_mul_f32 v[62:63], v[62:63], v[132:133] op_sel_hi:[1,0]
	v_pk_mul_f32 v[60:61], v[60:61], v[132:133] op_sel_hi:[1,0]
	v_pk_mul_f32 v[50:51], v[50:51], v[132:133] op_sel_hi:[1,0]
	v_pk_mul_f32 v[48:49], v[48:49], v[132:133] op_sel_hi:[1,0]
	v_pk_mul_f32 v[74:75], v[74:75], v[132:133] op_sel_hi:[1,0]
	v_pk_mul_f32 v[72:73], v[72:73], v[132:133] op_sel_hi:[1,0]
	v_pk_mul_f32 v[70:71], v[70:71], v[132:133] op_sel_hi:[1,0]
	v_pk_mul_f32 v[68:69], v[68:69], v[132:133] op_sel_hi:[1,0]
	v_sub_f32_e32 v126, v126, v133
	v_sub_f32_e32 v127, v127, v133
	v_sub_f32_e32 v128, v128, v133
	v_sub_f32_e32 v129, v129, v133
	v_sub_f32_e32 v130, v130, v133
	v_sub_f32_e32 v131, v131, v133
	v_sub_f32_e32 v138, v138, v133
	v_sub_f32_e32 v139, v139, v133
	v_sub_f32_e32 v140, v140, v133
	v_sub_f32_e32 v141, v141, v133
	v_sub_f32_e32 v144, v144, v133
	v_sub_f32_e32 v145, v145, v133
	v_sub_f32_e32 v146, v146, v133
	v_sub_f32_e32 v147, v147, v133

; DI void attn_phase(const Params& p, unsigned char* smem) {
;     ...
;             const int cur = st_ & 1;
;             if (st_ + 1 < nst) {
;                 const bool h2 = 2 * st_ + 3 < ntiles;
;                 const bf16_t* kb2 = kbase + (size_t)(st_ + 1) * 128 * 768; const bf16_t* vb2 = vbase + (st_ + 1) * 128;
;                 rk0 = *(const uint4*)(kb2 + ko0);
;                 if (kr1 < 64 || h2) rk1 = *(const uint4*)(kb2 + ko1);
;                 if (h2) rk2 = *(const uint4*)(kb2 + ko2);
;                 if (vch < 8 || h2) { rv0 = *(const uint4*)(vb2 + vo0); rv1 = *(const uint4*)(vb2 + vo1); }
;             }
; #pragma unroll
;             for (int hf = 0; hf < 2; ++hf) {
;                 if (2 * st_ + hf < wtiles) {
;                     const bf16_t* sK = sbuf + cur * BUF + hf * 64 * KST; const bf16_t* sV = sbuf + cur * BUF + 128 * KST + hf * 64;
;                     bf16x8 kf[4][3];
; #pragma unroll
;                     for (int kk = 0; kk < 4; ++kk)
; #pragma unroll
;                         for (int s = 0; s < 3; ++s) kf[kk][s] = *(const bf16x8*)(sK + (16 * kk + fr) * KST + 32 * s + 8 * g);
; #pragma unroll
;                     for (int qs = 0; qs < 2; ++qs) {
;                         f32x4 st[4];
;                         const float nm = -mrow[qs];
; #pragma unroll
;                         for (int kk = 0; kk < 4; ++kk) {
;                             st[kk] = (f32x4){nm, nm, nm, nm};
; #pragma unroll
;                             for (int s = 0; s < 3; ++s) st[kk] = MFMA16(kf[kk][s], qf[qs][s], st[kk]);
;                         }
;                         float mx = fmaxf(fmaxf(st[0][0], st[0][1]), fmaxf(st[0][2], st[0][3]));
; #pragma unroll
;                         for (int kk = 1; kk < 4; ++kk) mx = fmaxf(mx, fmaxf(fmaxf(st[kk][0], st[kk][1]), fmaxf(st[kk][2], st[kk][3])));
;                         const bool first = (st_ == 0 && hf == 0);
;                         if (first || __any(mx > 6.f)) {
;                             mx = fmaxf(mx, __shfl_xor(mx, 16)); mx = fmaxf(mx, __shfl_xor(mx, 32));
;                             const float shift = first ? mx : fmaxf(mx, 0.f);
;                             const float al = first ? 1.f : __builtin_amdgcn_exp2f(-shift);
;                             mrow[qs] += shift; lrow[qs] *= al;
; #pragma unroll
;                             for (int dt = 0; dt < 4; ++dt) ot[dt][qs] *= al;
.LBB0_943:
	s_add_i32 s14, s43, -1
	s_and_b32 s18, s14, 1
	s_mul_i32 s14, s18, 0xb400
	s_add_i32 s19, s14, 16
	v_cmp_lt_i32_e32 vcc, s44, v230
	v_add3_u32 v231, s19, v164, v218
	s_and_saveexec_b64 s[14:15], vcc
	s_cbranch_execz .LBB0_949
	v_xor_b32_e32 v132, 0x80000000, v203
	v_mov_b32_e32 v133, v132
	v_pk_mov_b32 v[134:135], v[132:133], v[132:133] op_sel:[0,0]
	ds_read_b128 v[112:115], v231
	ds_read_b128 v[116:119], v231 offset:64
	ds_read_b128 v[120:123], v231 offset:128
	ds_read_b128 v[100:103], v231 offset:3584
	ds_read_b128 v[104:107], v231 offset:3648
	ds_read_b128 v[108:111], v231 offset:3712
	ds_read_b128 v[96:99], v231 offset:7168
	ds_read_b128 v[92:95], v231 offset:7232
	ds_read_b128 v[88:91], v231 offset:7296
	ds_read_b128 v[84:87], v231 offset:10752
	ds_read_b128 v[80:83], v231 offset:10816
	ds_read_b128 v[76:79], v231 offset:10880
	s_waitcnt lgkmcnt(11)
	v_mfma_f32_16x16x32_bf16 v[124:127], v[112:115], v[4:7], v[132:135]
	s_waitcnt lgkmcnt(8)
	v_mfma_f32_16x16x32_bf16 v[128:131], v[100:103], v[4:7], v[132:135]
	v_mfma_f32_16x16x32_bf16 v[124:127], v[116:119], v[0:3], v[124:127]
	s_waitcnt lgkmcnt(5)
	v_mfma_f32_16x16x32_bf16 v[136:139], v[96:99], v[4:7], v[132:135]
	s_waitcnt lgkmcnt(2)
	v_mfma_f32_16x16x32_bf16 v[132:135], v[84:87], v[4:7], v[132:135]
	v_mfma_f32_16x16x32_bf16 v[128:131], v[104:107], v[0:3], v[128:131]
	v_mfma_f32_16x16x32_bf16 v[124:127], v[120:123], v[12:15], v[124:127]
	s_waitcnt lgkmcnt(1)
	v_mfma_f32_16x16x32_bf16 v[132:135], v[80:83], v[0:3], v[132:135]
	v_mfma_f32_16x16x32_bf16 v[136:139], v[92:95], v[0:3], v[136:139]
	v_mfma_f32_16x16x32_bf16 v[128:131], v[108:111], v[12:15], v[128:131]
	s_waitcnt lgkmcnt(0)
	v_mfma_f32_16x16x32_bf16 v[144:147], v[76:79], v[12:15], v[132:135]
	s_nop 3
	v_max3_f32 v132, v124, v125, v126
	v_mfma_f32_16x16x32_bf16 v[138:141], v[88:91], v[12:15], v[136:139]
	v_max3_f32 v133, v127, v128, v129
	v_max3_f32 v132, v132, v130, v131
	v_max3_f32 v134, v144, v145, v146
	v_max3_f32 v132, v132, v133, v134
	s_nop 3
	v_max3_f32 v133, v138, v139, v140
	v_max3_f32 v132, v132, v133, v141
	v_max_f32_e32 v132, v132, v147
	v_cmp_lt_f32_e32 vcc, s34, v132
	s_cbranch_vccz .LBB0_946
	v_and_b32_e32 v134, 64, v251
	v_xor_b32_e32 v133, 16, v251
	v_add_u32_e32 v134, 64, v134
	v_cmp_lt_i32_e32 vcc, v133, v134
	s_nop 1
	v_cndmask_b32_e32 v133, v251, v133, vcc
	v_lshlrev_b32_e32 v133, 2, v133
	ds_bpermute_b32 v133, v133, v132
	v_max_f32_e32 v132, v132, v132
	s_waitcnt lgkmcnt(0)
	v_max_f32_e32 v133, v133, v133
	v_max_f32_e32 v132, v132, v133
	v_xor_b32_e32 v133, 32, v251
	v_cmp_lt_i32_e32 vcc, v133, v134
	s_nop 1
	v_cndmask_b32_e32 v133, v251, v133, vcc
	v_lshlrev_b32_e32 v133, 2, v133
	ds_bpermute_b32 v133, v133, v132
	s_waitcnt lgkmcnt(0)
	v_max3_f32 v133, v132, v133, 0
	v_exp_f32_e64 v132, -v133
	v_add_f32_e32 v203, v203, v133
	v_sub_f32_e32 v124, v124, v133
	v_sub_f32_e32 v125, v125, v133
	v_mul_f32_e32 v200, v200, v132
	v_pk_mul_f32 v[62:63], v[62:63], v[132:133] op_sel_hi:[1,0]
	v_pk_mul_f32 v[60:61], v[60:61], v[132:133] op_sel_hi:[1,0]
	v_pk_mul_f32 v[50:51], v[50:51], v[132:133] op_sel_hi:[1,0]
	v_pk_mul_f32 v[48:49], v[48:49], v[132:133] op_sel_hi:[1,0]
	v_pk_mul_f32 v[74:75], v[74:75], v[132:133] op_sel_hi:[1,0]
	v_pk_mul_f32 v[72:73], v[72:73], v[132:133] op_sel_hi:[1,0]
	v_pk_mul_f32 v[70:71], v[70:71], v[132:133] op_sel_hi:[1,0]
	v_pk_mul_f32 v[68:69], v[68:69], v[132:133] op_sel_hi:[1,0]
	v_sub_f32_e32 v126, v126, v133
	v_sub_f32_e32 v127, v127, v133
	v_sub_f32_e32 v128, v128, v133
	v_sub_f32_e32 v129, v129, v133
	v_sub_f32_e32 v130, v130, v133
	v_sub_f32_e32 v131, v131, v133
	v_sub_f32_e32 v138, v138, v133
	v_sub_f32_e32 v139, v139, v133
	v_sub_f32_e32 v140, v140, v133
	v_sub_f32_e32 v141, v141, v133
	v_sub_f32_e32 v144, v144, v133
	v_sub_f32_e32 v145, v145, v133
	v_sub_f32_e32 v146, v146, v133
	v_sub_f32_e32 v147, v147, v133
; DI void attn_phase(const Params& p, unsigned char* smem) {
;     ...
;                         const float nm = -mrow[qs];
; #pragma unroll
;                         for (int kk = 0; kk < 4; ++kk) {
;                             st[kk] = (f32x4){nm, nm, nm, nm};
; #pragma unroll
;                             for (int s = 0; s < 3; ++s) st[kk] = MFMA16(kf[kk][s], qf[qs][s], st[kk]);
;                         }
;                         float mx = fmaxf(fmaxf(st[0][0], st[0][1]), fmaxf(st[0][2], st[0][3]));
; #pragma unroll
;                         for (int kk = 1; kk < 4; ++kk) mx = fmaxf(mx, fmaxf(fmaxf(st[kk][0], st[kk][1]), fmaxf(st[kk][2], st[kk][3])));
;                         const bool first = (st_ == 0 && hf == 0);
;                         if (first || __any(mx > 6.f)) {
;                             mx = fmaxf(mx, __shfl_xor(mx, 16)); mx = fmaxf(mx, __shfl_xor(mx, 32));
;                             const float shift = first ? mx : fmaxf(mx, 0.f);
;                             const float al = first ? 1.f : __builtin_amdgcn_exp2f(-shift);
;                             mrow[qs] += shift; lrow[qs] *= al;
; #pragma unroll
;                             for (int dt = 0; dt < 4; ++dt) ot[dt][qs] *= al;
; #pragma unroll
;                             for (int kk = 0; kk < 4; ++kk)
; #pragma unroll
;                                 for (int e = 0; e < 4; ++e) st[kk][e] -= shift;
;                         }
;                         float rs = 0.f;
; #pragma unroll
;                         for (int kk = 0; kk < 4; ++kk)
; #pragma unroll
;                             for (int e = 0; e < 4; ++e) { const float pv = __builtin_amdgcn_exp2f(st[kk][e]); st[kk][e] = pv; rs += pv; }
;                         lrow[qs] += rs;
; #pragma unroll
;                         for (int s2 = 0; s2 < 2; ++s2) {
;                             uint4 u; u.x = pack2(st[2 * s2][0], st[2 * s2][1]); u.y = pack2(st[2 * s2][2], st[2 * s2][3]);
;                             u.z = pack2(st[2 * s2 + 1][0], st[2 * s2 + 1][1]); u.w = pack2(st[2 * s2 + 1][2], st[2 * s2 + 1][3]);
;                             const bf16x8 pf = asbf(u);
; #pragma unroll
;                             for (int dt = 0; dt < 4; ++dt) {
;                                 const uint2 a = *(const uint2*)(sV + (16 * dt + fr) * VST + 32 * s2 + 4 * g), b = *(const uint2*)(sV + (16 * dt + fr) * VST + 32 * s2 + 16 + 4 * g);
.LBB0_946:
	v_add3_u32 v132, s19, v219, v217
	v_exp_f32_e32 v236, v128
	v_add_u32_e32 v142, 0x7000, v132
	v_add3_u32 v128, s19, v220, v217
	v_add3_u32 v132, s19, v221, v217
	v_add3_u32 v136, s19, v222, v217
	v_add_u32_e32 v152, 0x7000, v128
	v_add_u32_e32 v153, 0x7000, v132
	v_add_u32_e32 v154, 0x7000, v136
	v_exp_f32_e32 v232, v124
	v_exp_f32_e32 v233, v125
	v_exp_f32_e32 v234, v126
	v_exp_f32_e32 v235, v127
	v_exp_f32_e32 v237, v129
	v_exp_f32_e32 v238, v130
	v_exp_f32_e32 v239, v131
	ds_read2_b64 v[124:127], v142 offset1:4
	v_exp_f32_e32 v240, v138
	ds_read2_b64 v[128:131], v152 offset1:4
	ds_read2_b64 v[132:135], v153 offset1:4
	v_exp_f32_e32 v241, v139
	ds_read2_b64 v[136:139], v154 offset1:4
	v_cvt_pk_bf16_f32 v148, v232, v233
	v_cvt_pk_bf16_f32 v149, v234, v235
	v_cvt_pk_bf16_f32 v150, v236, v237
	v_cvt_pk_bf16_f32 v151, v238, v239
	v_exp_f32_e32 v242, v140
	v_exp_f32_e32 v243, v141
	s_waitcnt lgkmcnt(3)
	v_mfma_f32_16x16x32_bf16 v[60:63], v[124:127], v[148:151], v[60:63]
	v_exp_f32_e32 v244, v144
	ds_read2_b64 v[140:143], v142 offset0:8 offset1:12
	v_exp_f32_e32 v245, v145
	s_waitcnt lgkmcnt(3)
	v_mfma_f32_16x16x32_bf16 v[48:51], v[128:131], v[148:151], v[48:51]
	v_exp_f32_e32 v246, v146
	v_exp_f32_e32 v247, v147
	ds_read2_b64 v[144:147], v152 offset0:8 offset1:12
	s_waitcnt lgkmcnt(3)
	v_mfma_f32_16x16x32_bf16 v[72:75], v[132:135], v[148:151], v[72:75]
	v_cvt_pk_bf16_f32 v158, v240, v241
	v_cvt_pk_bf16_f32 v159, v242, v243
	v_cvt_pk_bf16_f32 v160, v244, v245
	s_waitcnt lgkmcnt(2)
	v_mfma_f32_16x16x32_bf16 v[68:71], v[136:139], v[148:151], v[68:71]
	ds_read2_b64 v[148:151], v153 offset0:8 offset1:12
	ds_read2_b64 v[152:155], v154 offset0:8 offset1:12
	v_cvt_pk_bf16_f32 v161, v246, v247
	s_waitcnt lgkmcnt(3)
	s_nop 0
	v_mfma_f32_16x16x32_bf16 v[60:63], v[140:143], v[158:161], v[60:63]
	s_waitcnt lgkmcnt(2)
	v_mfma_f32_16x16x32_bf16 v[48:51], v[144:147], v[158:161], v[48:51]
	s_waitcnt lgkmcnt(1)
	v_mfma_f32_16x16x32_bf16 v[72:75], v[148:151], v[158:161], v[72:75]
	s_waitcnt lgkmcnt(0)
	v_mfma_f32_16x16x32_bf16 v[68:71], v[152:155], v[158:161], v[68:71]
	v_xor_b32_e32 v158, 0x80000000, v202
	v_mov_b32_e32 v159, v158
	v_pk_mov_b32 v[160:161], v[158:159], v[158:159] op_sel:[0,0]
	s_nop 1
	v_mfma_f32_16x16x32_bf16 v[100:103], v[100:103], v[8:11], v[158:161]
	v_mfma_f32_16x16x32_bf16 v[112:115], v[112:115], v[8:11], v[158:161]
	v_mfma_f32_16x16x32_bf16 v[96:99], v[96:99], v[8:11], v[158:161]
	v_mfma_f32_16x16x32_bf16 v[84:87], v[84:87], v[8:11], v[158:161]
	v_mfma_f32_16x16x32_bf16 v[100:103], v[104:107], v[20:23], v[100:103]
	v_mfma_f32_16x16x32_bf16 v[112:115], v[116:119], v[20:23], v[112:115]
	v_mfma_f32_16x16x32_bf16 v[92:95], v[92:95], v[20:23], v[96:99]
	v_mfma_f32_16x16x32_bf16 v[80:83], v[80:83], v[20:23], v[84:87]
	v_mfma_f32_16x16x32_bf16 v[100:103], v[108:111], v[16:19], v[100:103]
	v_mfma_f32_16x16x32_bf16 v[112:115], v[120:123], v[16:19], v[112:115]
	v_mfma_f32_16x16x32_bf16 v[88:91], v[88:91], v[16:19], v[92:95]
	v_mfma_f32_16x16x32_bf16 v[76:79], v[76:79], v[16:19], v[80:83]
	s_nop 4
	v_max3_f32 v93, v100, v101, v102
	v_max3_f32 v94, v103, v112, v113
	v_max3_f32 v96, v114, v115, v88
	v_max3_f32 v93, v93, v94, v96
	v_max3_f32 v94, v89, v90, v91
	v_max3_f32 v96, v76, v77, v78
	v_max3_f32 v93, v93, v94, v96
	v_max_f32_e32 v80, v93, v79
	v_cmp_lt_f32_e32 vcc, s34, v80
	s_cbranch_vccz .LBB0_948
	v_and_b32_e32 v82, 64, v251
	v_xor_b32_e32 v81, 16, v251
	v_add_u32_e32 v82, 64, v82
	v_cmp_lt_i32_e32 vcc, v81, v82
	s_nop 1
	v_cndmask_b32_e32 v81, v251, v81, vcc
	v_lshlrev_b32_e32 v81, 2, v81
	ds_bpermute_b32 v81, v81, v80
	v_max_f32_e32 v80, v80, v80
	s_waitcnt lgkmcnt(0)
	v_max_f32_e32 v81, v81, v81
	v_max_f32_e32 v80, v80, v81
	v_xor_b32_e32 v81, 32, v251
	v_cmp_lt_i32_e32 vcc, v81, v82
	s_nop 1
	v_cndmask_b32_e32 v81, v251, v81, vcc
	v_lshlrev_b32_e32 v81, 2, v81
	ds_bpermute_b32 v81, v81, v80
	s_waitcnt lgkmcnt(0)
	v_max3_f32 v81, v80, v81, 0
	v_exp_f32_e64 v80, -v81
	v_add_f32_e32 v202, v202, v81
	v_sub_f32_e32 v112, v112, v81
	v_sub_f32_e32 v113, v113, v81
	v_mul_f32_e32 v201, v201, v80
	v_pk_mul_f32 v[66:67], v[66:67], v[80:81] op_sel_hi:[1,0]
	v_pk_mul_f32 v[64:65], v[64:65], v[80:81] op_sel_hi:[1,0]
	v_pk_mul_f32 v[58:59], v[58:59], v[80:81] op_sel_hi:[1,0]
	v_pk_mul_f32 v[56:57], v[56:57], v[80:81] op_sel_hi:[1,0]
	v_pk_mul_f32 v[54:55], v[54:55], v[80:81] op_sel_hi:[1,0]
	v_pk_mul_f32 v[52:53], v[52:53], v[80:81] op_sel_hi:[1,0]
	v_pk_mul_f32 v[46:47], v[46:47], v[80:81] op_sel_hi:[1,0]
	v_pk_mul_f32 v[44:45], v[44:45], v[80:81] op_sel_hi:[1,0]
	v_sub_f32_e32 v114, v114, v81
	v_sub_f32_e32 v115, v115, v81
	v_sub_f32_e32 v100, v100, v81
	v_sub_f32_e32 v101, v101, v81
	v_sub_f32_e32 v102, v102, v81
	v_sub_f32_e32 v103, v103, v81
	v_sub_f32_e32 v88, v88, v81
	v_sub_f32_e32 v89, v89, v81
	v_sub_f32_e32 v90, v90, v81
	v_sub_f32_e32 v91, v91, v81
	v_sub_f32_e32 v76, v76, v81
	v_sub_f32_e32 v77, v77, v81
	v_sub_f32_e32 v78, v78, v81
	v_sub_f32_e32 v79, v79, v81

; #define MFMA16(a, b, c) __builtin_amdgcn_mfma_f32_16x16x32_bf16((a), (b), (c), 0, 0, 0)
; DI void attn_phase(const Params& p, unsigned char* smem) {
;     ...
;                 if (2 * st_ + hf < wtiles) {
;                     const bf16_t* sK = sbuf + cur * BUF + hf * 64 * KST; const bf16_t* sV = sbuf + cur * BUF + 128 * KST + hf * 64;
;                     bf16x8 kf[4][3];
; #pragma unroll
;                     for (int kk = 0; kk < 4; ++kk)
; #pragma unroll
;                         for (int s = 0; s < 3; ++s) kf[kk][s] = *(const bf16x8*)(sK + (16 * kk + fr) * KST + 32 * s + 8 * g);
; #pragma unroll
;                     for (int qs = 0; qs < 2; ++qs) {
;                         f32x4 st[4];
;                         const float nm = -mrow[qs];
; #pragma unroll
;                         for (int kk = 0; kk < 4; ++kk) {
;                             st[kk] = (f32x4){nm, nm, nm, nm};
; #pragma unroll
;                             for (int s = 0; s < 3; ++s) st[kk] = MFMA16(kf[kk][s], qf[qs][s], st[kk]);
;                         }
;                         float mx = fmaxf(fmaxf(st[0][0], st[0][1]), fmaxf(st[0][2], st[0][3]));
; #pragma unroll
;                         for (int kk = 1; kk < 4; ++kk) mx = fmaxf(mx, fmaxf(fmaxf(st[kk][0], st[kk][1]), fmaxf(st[kk][2], st[kk][3])));
;                         const bool first = (st_ == 0 && hf == 0);
;                         if (first || __any(mx > 6.f)) {
;                             mx = fmaxf(mx, __shfl_xor(mx, 16)); mx = fmaxf(mx, __shfl_xor(mx, 32));
;                             const float shift = first ? mx : fmaxf(mx, 0.f);
;                             const float al = first ? 1.f : __builtin_amdgcn_exp2f(-shift);
;                             mrow[qs] += shift; lrow[qs] *= al;
; #pragma unroll
;                             for (int dt = 0; dt < 4; ++dt) ot[dt][qs] *= al;
; #pragma unroll
;                             for (int kk = 0; kk < 4; ++kk)
; #pragma unroll
;                                 for (int e = 0; e < 4; ++e) st[kk][e] -= shift;
.LBB0_949:
	s_or_b64 exec, exec, s[14:15]
	s_add_i32 s14, s44, 1
	v_cmp_lt_i32_e32 vcc, s14, v230
	s_and_saveexec_b64 s[14:15], vcc
	s_cbranch_execz .LBB0_955
	v_xor_b32_e32 v132, 0x80000000, v203
	v_mov_b32_e32 v133, v132
	v_pk_mov_b32 v[134:135], v[132:133], v[132:133] op_sel:[0,0]
	ds_read_b128 v[112:115], v231 offset:14336
	ds_read_b128 v[116:119], v231 offset:14400
	ds_read_b128 v[120:123], v231 offset:14464
	ds_read_b128 v[100:103], v231 offset:17920
	ds_read_b128 v[104:107], v231 offset:17984
	ds_read_b128 v[108:111], v231 offset:18048
	ds_read_b128 v[96:99], v231 offset:21504
	ds_read_b128 v[92:95], v231 offset:21568
	ds_read_b128 v[88:91], v231 offset:21632
	ds_read_b128 v[84:87], v231 offset:25088
	ds_read_b128 v[80:83], v231 offset:25152
	ds_read_b128 v[76:79], v231 offset:25216
	s_waitcnt lgkmcnt(11)
	v_mfma_f32_16x16x32_bf16 v[124:127], v[112:115], v[4:7], v[132:135]
	s_waitcnt lgkmcnt(8)
	v_mfma_f32_16x16x32_bf16 v[128:131], v[100:103], v[4:7], v[132:135]
	v_mfma_f32_16x16x32_bf16 v[124:127], v[116:119], v[0:3], v[124:127]
	s_waitcnt lgkmcnt(5)
	v_mfma_f32_16x16x32_bf16 v[136:139], v[96:99], v[4:7], v[132:135]
	s_waitcnt lgkmcnt(2)
	v_mfma_f32_16x16x32_bf16 v[132:135], v[84:87], v[4:7], v[132:135]
	v_mfma_f32_16x16x32_bf16 v[128:131], v[104:107], v[0:3], v[128:131]
	v_mfma_f32_16x16x32_bf16 v[124:127], v[120:123], v[12:15], v[124:127]
	s_waitcnt lgkmcnt(1)
	v_mfma_f32_16x16x32_bf16 v[132:135], v[80:83], v[0:3], v[132:135]
	v_mfma_f32_16x16x32_bf16 v[136:139], v[92:95], v[0:3], v[136:139]
	v_mfma_f32_16x16x32_bf16 v[128:131], v[108:111], v[12:15], v[128:131]
	s_waitcnt lgkmcnt(0)
	v_mfma_f32_16x16x32_bf16 v[144:147], v[76:79], v[12:15], v[132:135]
	s_nop 3
	v_max3_f32 v132, v124, v125, v126
	v_mfma_f32_16x16x32_bf16 v[138:141], v[88:91], v[12:15], v[136:139]
	v_max3_f32 v133, v127, v128, v129
	v_max3_f32 v132, v132, v130, v131
	v_max3_f32 v134, v144, v145, v146
	v_max3_f32 v132, v132, v133, v134
	s_nop 3
	v_max3_f32 v133, v138, v139, v140
	v_max3_f32 v132, v132, v133, v141
	v_max_f32_e32 v132, v132, v147
	v_cmp_lt_f32_e32 vcc, s34, v132
	s_cbranch_vccz .LBB0_952
	v_and_b32_e32 v134, 64, v251
	v_xor_b32_e32 v133, 16, v251
	v_add_u32_e32 v134, 64, v134
	v_cmp_lt_i32_e32 vcc, v133, v134
	s_nop 1
	v_cndmask_b32_e32 v133, v251, v133, vcc
	v_lshlrev_b32_e32 v133, 2, v133
	ds_bpermute_b32 v133, v133, v132
	v_max_f32_e32 v132, v132, v132
	s_waitcnt lgkmcnt(0)
	v_max_f32_e32 v133, v133, v133
	v_max_f32_e32 v132, v132, v133
	v_xor_b32_e32 v133, 32, v251
	v_cmp_lt_i32_e32 vcc, v133, v134
	s_nop 1
	v_cndmask_b32_e32 v133, v251, v133, vcc
	v_lshlrev_b32_e32 v133, 2, v133
	ds_bpermute_b32 v133, v133, v132
	s_waitcnt lgkmcnt(0)
	v_max3_f32 v133, v132, v133, 0
	v_exp_f32_e64 v132, -v133
	v_add_f32_e32 v203, v203, v133
	v_sub_f32_e32 v124, v124, v133
	v_sub_f32_e32 v125, v125, v133
	v_mul_f32_e32 v200, v200, v132
	v_pk_mul_f32 v[62:63], v[62:63], v[132:133] op_sel_hi:[1,0]
	v_pk_mul_f32 v[60:61], v[60:61], v[132:133] op_sel_hi:[1,0]
	v_pk_mul_f32 v[50:51], v[50:51], v[132:133] op_sel_hi:[1,0]
	v_pk_mul_f32 v[48:49], v[48:49], v[132:133] op_sel_hi:[1,0]
	v_pk_mul_f32 v[74:75], v[74:75], v[132:133] op_sel_hi:[1,0]
	v_pk_mul_f32 v[72:73], v[72:73], v[132:133] op_sel_hi:[1,0]
	v_pk_mul_f32 v[70:71], v[70:71], v[132:133] op_sel_hi:[1,0]
	v_pk_mul_f32 v[68:69], v[68:69], v[132:133] op_sel_hi:[1,0]
	v_sub_f32_e32 v126, v126, v133
	v_sub_f32_e32 v127, v127, v133
	v_sub_f32_e32 v128, v128, v133
	v_sub_f32_e32 v129, v129, v133
	v_sub_f32_e32 v130, v130, v133
	v_sub_f32_e32 v131, v131, v133
	v_sub_f32_e32 v138, v138, v133
	v_sub_f32_e32 v139, v139, v133
	v_sub_f32_e32 v140, v140, v133
	v_sub_f32_e32 v141, v141, v133
	v_sub_f32_e32 v144, v144, v133
	v_sub_f32_e32 v145, v145, v133
	v_sub_f32_e32 v146, v146, v133
	v_sub_f32_e32 v147, v147, v133
; DI void attn_phase(const Params& p, unsigned char* smem) {
;     ...
;                         const float nm = -mrow[qs];
; #pragma unroll
;                         for (int kk = 0; kk < 4; ++kk) {
;                             st[kk] = (f32x4){nm, nm, nm, nm};
; #pragma unroll
;                             for (int s = 0; s < 3; ++s) st[kk] = MFMA16(kf[kk][s], qf[qs][s], st[kk]);
;                         }
;                         float mx = fmaxf(fmaxf(st[0][0], st[0][1]), fmaxf(st[0][2], st[0][3]));
; #pragma unroll
;                         for (int kk = 1; kk < 4; ++kk) mx = fmaxf(mx, fmaxf(fmaxf(st[kk][0], st[kk][1]), fmaxf(st[kk][2], st[kk][3])));
;                         const bool first = (st_ == 0 && hf == 0);
;                         if (first || __any(mx > 6.f)) {
;                             mx = fmaxf(mx, __shfl_xor(mx, 16)); mx = fmaxf(mx, __shfl_xor(mx, 32));
;                             const float shift = first ? mx : fmaxf(mx, 0.f);
;                             const float al = first ? 1.f : __builtin_amdgcn_exp2f(-shift);
;                             mrow[qs] += shift; lrow[qs] *= al;
; #pragma unroll
;                             for (int dt = 0; dt < 4; ++dt) ot[dt][qs] *= al;
; #pragma unroll
;                             for (int kk = 0; kk < 4; ++kk)
; #pragma unroll
;                                 for (int e = 0; e < 4; ++e) st[kk][e] -= shift;
;                         }
;                         float rs = 0.f;
; #pragma unroll
;                         for (int kk = 0; kk < 4; ++kk)
; #pragma unroll
;                             for (int e = 0; e < 4; ++e) { const float pv = __builtin_amdgcn_exp2f(st[kk][e]); st[kk][e] = pv; rs += pv; }
;                         lrow[qs] += rs;
; #pragma unroll
;                         for (int s2 = 0; s2 < 2; ++s2) {
;                             uint4 u; u.x = pack2(st[2 * s2][0], st[2 * s2][1]); u.y = pack2(st[2 * s2][2], st[2 * s2][3]);
;                             u.z = pack2(st[2 * s2 + 1][0], st[2 * s2 + 1][1]); u.w = pack2(st[2 * s2 + 1][2], st[2 * s2 + 1][3]);
;                             const bf16x8 pf = asbf(u);
; #pragma unroll
;                             for (int dt = 0; dt < 4; ++dt) {
;                                 const uint2 a = *(const uint2*)(sV + (16 * dt + fr) * VST + 32 * s2 + 4 * g), b = *(const uint2*)(sV + (16 * dt + fr) * VST + 32 * s2 + 16 + 4 * g);
.LBB0_952:
	v_add3_u32 v132, s19, v219, v217
	v_exp_f32_e32 v235, v128
	v_add_u32_e32 v142, 0x7000, v132
	v_add3_u32 v128, s19, v220, v217
	v_add3_u32 v132, s19, v221, v217
	v_add3_u32 v136, s19, v222, v217
	v_add_u32_e32 v152, 0x7000, v128
	v_add_u32_e32 v153, 0x7000, v132
	v_add_u32_e32 v154, 0x7000, v136
	v_exp_f32_e32 v231, v124
	v_exp_f32_e32 v232, v125
	v_exp_f32_e32 v233, v126
	v_exp_f32_e32 v234, v127
	v_exp_f32_e32 v236, v129
	v_exp_f32_e32 v237, v130
	v_exp_f32_e32 v238, v131
	ds_read2_b64 v[124:127], v142 offset0:16 offset1:20
	v_exp_f32_e32 v239, v138
	ds_read2_b64 v[128:131], v152 offset0:16 offset1:20
	ds_read2_b64 v[132:135], v153 offset0:16 offset1:20
	v_exp_f32_e32 v240, v139
	ds_read2_b64 v[136:139], v154 offset0:16 offset1:20
	v_cvt_pk_bf16_f32 v148, v231, v232
	v_cvt_pk_bf16_f32 v149, v233, v234
	v_cvt_pk_bf16_f32 v150, v235, v236
	v_cvt_pk_bf16_f32 v151, v237, v238
	v_exp_f32_e32 v241, v140
	v_exp_f32_e32 v242, v141
	s_waitcnt lgkmcnt(3)
	v_mfma_f32_16x16x32_bf16 v[60:63], v[124:127], v[148:151], v[60:63]
	v_exp_f32_e32 v243, v144
	ds_read2_b64 v[140:143], v142 offset0:24 offset1:28
	v_exp_f32_e32 v244, v145
	s_waitcnt lgkmcnt(3)
	v_mfma_f32_16x16x32_bf16 v[48:51], v[128:131], v[148:151], v[48:51]
	v_exp_f32_e32 v245, v146
	v_exp_f32_e32 v246, v147
	ds_read2_b64 v[144:147], v152 offset0:24 offset1:28
	s_waitcnt lgkmcnt(3)
	v_mfma_f32_16x16x32_bf16 v[72:75], v[132:135], v[148:151], v[72:75]
	v_cvt_pk_bf16_f32 v158, v239, v240
	v_cvt_pk_bf16_f32 v159, v241, v242
	v_cvt_pk_bf16_f32 v160, v243, v244
	s_waitcnt lgkmcnt(2)
	v_mfma_f32_16x16x32_bf16 v[68:71], v[136:139], v[148:151], v[68:71]
	ds_read2_b64 v[148:151], v153 offset0:24 offset1:28
	ds_read2_b64 v[152:155], v154 offset0:24 offset1:28
	v_cvt_pk_bf16_f32 v161, v245, v246
	s_waitcnt lgkmcnt(3)
	s_nop 0
	v_mfma_f32_16x16x32_bf16 v[60:63], v[140:143], v[158:161], v[60:63]
	s_waitcnt lgkmcnt(2)
	v_mfma_f32_16x16x32_bf16 v[48:51], v[144:147], v[158:161], v[48:51]
	s_waitcnt lgkmcnt(1)
	v_mfma_f32_16x16x32_bf16 v[72:75], v[148:151], v[158:161], v[72:75]
	s_waitcnt lgkmcnt(0)
	v_mfma_f32_16x16x32_bf16 v[68:71], v[152:155], v[158:161], v[68:71]
	v_xor_b32_e32 v158, 0x80000000, v202
	v_mov_b32_e32 v159, v158
	v_pk_mov_b32 v[160:161], v[158:159], v[158:159] op_sel:[0,0]
	s_nop 1
	v_mfma_f32_16x16x32_bf16 v[100:103], v[100:103], v[8:11], v[158:161]
	v_mfma_f32_16x16x32_bf16 v[112:115], v[112:115], v[8:11], v[158:161]
	v_mfma_f32_16x16x32_bf16 v[96:99], v[96:99], v[8:11], v[158:161]
	v_mfma_f32_16x16x32_bf16 v[84:87], v[84:87], v[8:11], v[158:161]
	v_mfma_f32_16x16x32_bf16 v[100:103], v[104:107], v[20:23], v[100:103]
	v_mfma_f32_16x16x32_bf16 v[112:115], v[116:119], v[20:23], v[112:115]
	v_mfma_f32_16x16x32_bf16 v[92:95], v[92:95], v[20:23], v[96:99]
	v_mfma_f32_16x16x32_bf16 v[80:83], v[80:83], v[20:23], v[84:87]
	v_mfma_f32_16x16x32_bf16 v[100:103], v[108:111], v[16:19], v[100:103]
	v_mfma_f32_16x16x32_bf16 v[112:115], v[120:123], v[16:19], v[112:115]
	v_mfma_f32_16x16x32_bf16 v[88:91], v[88:91], v[16:19], v[92:95]
	v_mfma_f32_16x16x32_bf16 v[76:79], v[76:79], v[16:19], v[80:83]
	s_nop 4
	v_max3_f32 v93, v100, v101, v102
	v_max3_f32 v94, v103, v112, v113
	v_max3_f32 v96, v114, v115, v88
	v_max3_f32 v93, v93, v94, v96
	v_max3_f32 v94, v89, v90, v91
	v_max3_f32 v96, v76, v77, v78
	v_max3_f32 v93, v93, v94, v96
	v_max_f32_e32 v80, v93, v79
	v_cmp_lt_f32_e32 vcc, s34, v80
	s_cbranch_vccz .LBB0_954
	v_and_b32_e32 v82, 64, v251
	v_xor_b32_e32 v81, 16, v251
	v_add_u32_e32 v82, 64, v82
	v_cmp_lt_i32_e32 vcc, v81, v82
	s_nop 1
	v_cndmask_b32_e32 v81, v251, v81, vcc
	v_lshlrev_b32_e32 v81, 2, v81
	ds_bpermute_b32 v81, v81, v80
	v_max_f32_e32 v80, v80, v80
	s_waitcnt lgkmcnt(0)
	v_max_f32_e32 v81, v81, v81
	v_max_f32_e32 v80, v80, v81
	v_xor_b32_e32 v81, 32, v251
	v_cmp_lt_i32_e32 vcc, v81, v82
	s_nop 1
	v_cndmask_b32_e32 v81, v251, v81, vcc
	v_lshlrev_b32_e32 v81, 2, v81
	ds_bpermute_b32 v81, v81, v80
	s_waitcnt lgkmcnt(0)
	v_max3_f32 v81, v80, v81, 0
	v_exp_f32_e64 v80, -v81
	v_add_f32_e32 v202, v202, v81
	v_sub_f32_e32 v112, v112, v81
	v_sub_f32_e32 v113, v113, v81
	v_mul_f32_e32 v201, v201, v80
	v_pk_mul_f32 v[66:67], v[66:67], v[80:81] op_sel_hi:[1,0]
	v_pk_mul_f32 v[64:65], v[64:65], v[80:81] op_sel_hi:[1,0]
	v_pk_mul_f32 v[58:59], v[58:59], v[80:81] op_sel_hi:[1,0]
	v_pk_mul_f32 v[56:57], v[56:57], v[80:81] op_sel_hi:[1,0]
	v_pk_mul_f32 v[54:55], v[54:55], v[80:81] op_sel_hi:[1,0]
	v_pk_mul_f32 v[52:53], v[52:53], v[80:81] op_sel_hi:[1,0]
	v_pk_mul_f32 v[46:47], v[46:47], v[80:81] op_sel_hi:[1,0]
	v_pk_mul_f32 v[44:45], v[44:45], v[80:81] op_sel_hi:[1,0]
	v_sub_f32_e32 v114, v114, v81
	v_sub_f32_e32 v115, v115, v81
	v_sub_f32_e32 v100, v100, v81
	v_sub_f32_e32 v101, v101, v81
	v_sub_f32_e32 v102, v102, v81
	v_sub_f32_e32 v103, v103, v81
	v_sub_f32_e32 v88, v88, v81
	v_sub_f32_e32 v89, v89, v81
	v_sub_f32_e32 v90, v90, v81
	v_sub_f32_e32 v91, v91, v81
	v_sub_f32_e32 v76, v76, v81
	v_sub_f32_e32 v77, v77, v81
	v_sub_f32_e32 v78, v78, v81
	v_sub_f32_e32 v79, v79, v81
